# SWA cross-item software pipeline: next item's staging loads issued in the second head pass after its last VMEM wait
# speedup vs baseline: 1.0010x; 1.0010x over previous
.LBB0_680:
	s_and_b32 s4, s22, 1
	s_lshl_b32 s5, s22, 6
	s_and_b32 s6, s5, 0xffffff80
	s_cmp_lt_i32 s6, 0x10000
	s_movk_i32 s7, 0xf80
	s_cselect_b32 s7, s7, 0x1f80
	s_movk_i32 s8, 0x2000
	s_cselect_b32 s8, 0x1000, s8
	s_and_b32 s7, s7, s5
	v_lshrrev_b32_e32 v0, 3, v195
	v_bfe_u32 v1, v195, 2, 1
	v_and_b32_e32 v2, 3, v195
	v_lshlrev_b32_e32 v3, 6, v1
	v_lshl_or_b32 v3, v2, 4, v3
	v_mul_u32_u24_e32 v4, 0x28000, v0
	v_add_u32_e32 v146, v4, v3
	v_lshrrev_b32_e32 v4, 1, v3
	v_mul_u32_u24_e32 v4, 0x88, v4
	v_lshl_add_u32 v147, v0, 1, v4
	v_and_b32_e32 v4, 35, v0
	v_bfe_u32 v5, v0, 2, 1
	v_lshl_or_b32 v4, v5, 4, v4
	v_bfe_u32 v5, v0, 3, 2
	v_lshl_or_b32 v4, v5, 2, v4
	v_mul_u32_u24_e32 v4, 0x310, v4
	v_add_u32_e32 v206, v4, v3
	s_lshl_b32 s9, s6, 1
	s_mul_i32 s10, s4, 0xa00000
	s_add_u32 s9, s9, s10
	v_readlane_b32 s10, v254, 9
	v_readlane_b32 s11, v254, 10
	s_add_u32 s10, s10, s9
	s_addc_u32 s11, s11, 0
	v_readlane_b32 s12, v254, 11
	v_readlane_b32 s13, v254, 12
	s_add_u32 s12, s12, s9
	s_addc_u32 s13, s13, 0
	v_readlane_b32 s2, v253, 5
	s_nop 1
	s_cmp_lg_u32 s22, s2
	s_cbranch_scc1 .Lswa_hi_done
	s_nop 1
	global_load_dwordx4 v[156:159], v146, s[10:11]
	global_load_dwordx4 v[160:163], v146, s[10:11] offset:128
	global_load_dwordx4 v[180:183], v146, s[12:13]
	global_load_dwordx4 v[184:187], v146, s[12:13] offset:128
	s_cmp_lg_u32 s7, 0
	s_cbranch_scc0 .Lswa_lo_zero
	global_load_dwordx4 v[148:151], v146, s[10:11] offset:-256
	global_load_dwordx4 v[152:155], v146, s[10:11] offset:-128
	global_load_dwordx4 v[172:175], v146, s[12:13] offset:-256
	global_load_dwordx4 v[176:179], v146, s[12:13] offset:-128
	s_branch .Lswa_lo_done

.LBB0_700:
	s_or_b64 exec, exec, s[18:19]
	s_waitcnt vmcnt(0)
	s_cmp_eq_u32 s97, 0
	s_cbranch_scc1 .Lswp_done
	v_readlane_b32 s98, v253, 0
	s_nop 1
	s_add_i32 s98, s22, s98
	s_cmpk_gt_i32 s98, 0x4ff
	s_cbranch_scc1 .Lswp_done
	s_lshl_b32 s99, s98, 6
	s_and_b32 s100, s99, 0xffffff80
	s_cmp_lt_i32 s100, 0x10000
	s_movk_i32 s98, 0x2000
	s_cselect_b32 s98, 0x1000, s98
	s_movk_i32 s101, 0x1f80
	s_cselect_b32 s101, 0xf80, s101
	s_and_b32 s101, s101, s99
	s_add_i32 s99, s101, 0x80
	s_cmp_lt_i32 s99, s98
	s_cselect_b32 s98, 2, 0
	s_cmp_lg_u32 s101, 0
	s_cselect_b32 s99, 1, 0
	s_or_b32 s98, s98, s99
	s_lshl_b32 s100, s100, 1
	s_and_b32 s99, s22, 1
	s_mul_i32 s99, s99, 0xa00000
	s_add_u32 s99, s100, s99
	v_readlane_b32 s100, v254, 9
	v_readlane_b32 s101, v254, 10
	s_nop 1
	s_add_u32 s100, s100, s99
	s_addc_u32 s101, s101, 0
	s_nop 3
	global_load_dwordx4 v[156:159], v146, s[100:101]
	global_load_dwordx4 v[160:163], v146, s[100:101] offset:128
	s_bitcmp1_b32 s98, 0
	s_cbranch_scc0 .Lswp_klo0
	global_load_dwordx4 v[148:151], v146, s[100:101] offset:-256
	global_load_dwordx4 v[152:155], v146, s[100:101] offset:-128
	s_branch .Lswp_klo1

.Lswp_klo1:
	s_bitcmp1_b32 s98, 1
	s_cbranch_scc0 .Lswp_khi0
	global_load_dwordx4 v[164:167], v146, s[100:101] offset:256
	global_load_dwordx4 v[168:171], v146, s[100:101] offset:384
	s_branch .Lswp_khi1

.Lswp_khi1:
	v_readlane_b32 s100, v254, 11
	v_readlane_b32 s101, v254, 12
	s_nop 1
	s_add_u32 s100, s100, s99
	s_addc_u32 s101, s101, 0
	s_nop 3
	global_load_dwordx4 v[180:183], v146, s[100:101]
	global_load_dwordx4 v[184:187], v146, s[100:101] offset:128
	s_bitcmp1_b32 s98, 0
	s_cbranch_scc0 .Lswp_vlo0
	global_load_dwordx4 v[172:175], v146, s[100:101] offset:-256
	global_load_dwordx4 v[176:179], v146, s[100:101] offset:-128
	s_branch .Lswp_vlo1
.Lswp_vlo0:
	v_mov_b32_e32 v172, 0
	v_mov_b32_e32 v173, 0
	v_mov_b32_e32 v174, 0
	v_mov_b32_e32 v175, 0
	v_mov_b32_e32 v176, 0
	v_mov_b32_e32 v177, 0
	v_mov_b32_e32 v178, 0
	v_mov_b32_e32 v179, 0
.Lswp_vlo1:
	s_bitcmp1_b32 s98, 1
	s_cbranch_scc0 .Lswp_vhi0
	global_load_dwordx4 v[188:191], v146, s[100:101] offset:256
	global_load_dwordx4 v[208:211], v146, s[100:101] offset:384
	s_branch .Lswp_vhi1
.Lswp_vhi0:
	v_mov_b32_e32 v188, 0
	v_mov_b32_e32 v189, 0
	v_mov_b32_e32 v190, 0
	v_mov_b32_e32 v191, 0
	v_mov_b32_e32 v208, 0
	v_mov_b32_e32 v209, 0
	v_mov_b32_e32 v210, 0
	v_mov_b32_e32 v211, 0
.Lswp_vhi1:
.Lswp_done:
	v_max3_f32 v0, v19, v28, v24
	v_max3_f32 v0, v0, v26, v25
	v_max3_f32 v0, v0, v29, v27
	v_max3_f32 v0, v0, v31, v30
	v_max3_f32 v0, v0, v33, v32
	v_max3_f32 v0, v0, v35, v34
	v_max3_f32 v0, v0, v38, v36
	v_max3_f32 v0, v0, v40, v39
	v_max3_f32 v0, v0, v43, v41
	v_max3_f32 v0, v0, v45, v44
	v_max3_f32 v0, v0, v47, v46
	v_max3_f32 v0, v0, v49, v48
	v_max3_f32 v0, v0, v51, v50
	v_max3_f32 v0, v0, v53, v52
	v_max3_f32 v0, v0, v59, v58
	v_max3_f32 v0, v0, v66, v67
	v_max3_f32 v0, v0, v95, v94
	v_max3_f32 v0, v0, v97, v96
	v_max3_f32 v0, v0, v99, v98
	v_max3_f32 v0, v0, v101, v100
	v_max3_f32 v0, v0, v103, v102
	v_max3_f32 v0, v0, v105, v104
	v_max3_f32 v0, v0, v107, v106
	v_max3_f32 v0, v0, v109, v108
	v_max3_f32 v0, v0, v111, v110
	v_max3_f32 v0, v0, v113, v112
	v_max3_f32 v0, v0, v115, v114
	v_max3_f32 v0, v0, v117, v116
	v_max3_f32 v0, v0, v119, v118
	v_max3_f32 v0, v0, v121, v120
	v_max3_f32 v0, v0, v123, v122
	v_max3_f32 v0, v0, v125, v124
	v_max3_f32 v0, v0, v127, v126
	v_add_u32_e32 v1, 64, v242
	v_max3_f32 v0, v0, v129, v128
	v_cmp_lt_i32_e32 vcc, v237, v1
	v_max3_f32 v0, v0, v6, v7
	v_max3_f32 v0, v0, v131, v130
	v_cndmask_b32_e32 v2, v220, v237, vcc
	v_lshlrev_b32_e32 v132, 2, v2
	ds_bpermute_b32 v2, v132, v0
	v_cmp_lt_i32_e32 vcc, v236, v1
	s_lshl_b32 s0, s25, 6
	s_lshl_b32 s0, s0, 1
	s_waitcnt lgkmcnt(0)
	v_max_f32_e32 v2, v2, v2
	v_cndmask_b32_e32 v1, v220, v236, vcc
	v_max_f32_e32 v0, v0, v2
	v_lshlrev_b32_e32 v134, 2, v1
	ds_bpermute_b32 v1, v134, v0
	s_xor_b64 s[18:19], s[20:21], -1
	s_mov_b32 s97, 1
	s_mov_b64 s[20:21], 0
	s_and_b64 vcc, exec, s[18:19]
	s_waitcnt lgkmcnt(0)
	v_max_f32_e32 v1, v1, v1
	v_max_f32_e32 v133, v0, v1
	v_sub_f32_e32 v1, v24, v133
	v_mul_f32_e32 v1, 0x3fb8aa3b, v1
	v_exp_f32_e32 v71, v1
	v_sub_f32_e32 v1, v26, v133
	v_mul_f32_e32 v1, 0x3fb8aa3b, v1
	v_exp_f32_e32 v78, v1
	v_sub_f32_e32 v1, v25, v133
	v_mul_f32_e32 v1, 0x3fb8aa3b, v1
	v_exp_f32_e32 v79, v1
	v_sub_f32_e32 v1, v29, v133
	v_mul_f32_e32 v1, 0x3fb8aa3b, v1
	v_exp_f32_e32 v82, v1
	v_sub_f32_e32 v1, v27, v133
	v_mul_f32_e32 v1, 0x3fb8aa3b, v1
	v_exp_f32_e32 v83, v1
	v_sub_f32_e32 v1, v31, v133
	v_mul_f32_e32 v1, 0x3fb8aa3b, v1
	v_exp_f32_e32 v84, v1
	v_sub_f32_e32 v1, v30, v133
	v_mul_f32_e32 v1, 0x3fb8aa3b, v1
	v_exp_f32_e32 v85, v1
	v_sub_f32_e32 v1, v33, v133
	v_mul_f32_e32 v1, 0x3fb8aa3b, v1
	v_exp_f32_e32 v64, v1
	v_sub_f32_e32 v1, v32, v133
	v_mul_f32_e32 v1, 0x3fb8aa3b, v1
	v_exp_f32_e32 v65, v1
	v_sub_f32_e32 v1, v35, v133
	v_mul_f32_e32 v1, 0x3fb8aa3b, v1
	v_exp_f32_e32 v72, v1
	v_sub_f32_e32 v1, v34, v133
	v_mul_f32_e32 v1, 0x3fb8aa3b, v1
	v_exp_f32_e32 v73, v1
	v_sub_f32_e32 v1, v38, v133
	v_mul_f32_e32 v1, 0x3fb8aa3b, v1
	v_exp_f32_e32 v76, v1
	v_sub_f32_e32 v1, v36, v133
	v_mul_f32_e32 v1, 0x3fb8aa3b, v1
	v_exp_f32_e32 v77, v1
	v_sub_f32_e32 v1, v40, v133
	v_mul_f32_e32 v1, 0x3fb8aa3b, v1
	v_exp_f32_e32 v80, v1
	v_sub_f32_e32 v1, v39, v133
	v_mul_f32_e32 v1, 0x3fb8aa3b, v1
	v_exp_f32_e32 v81, v1
	v_sub_f32_e32 v1, v43, v133
	v_mul_f32_e32 v1, 0x3fb8aa3b, v1
	v_exp_f32_e32 v56, v1
	v_sub_f32_e32 v1, v41, v133
	v_mul_f32_e32 v1, 0x3fb8aa3b, v1
	v_exp_f32_e32 v57, v1
	v_sub_f32_e32 v1, v45, v133
	v_mul_f32_e32 v1, 0x3fb8aa3b, v1
	v_exp_f32_e32 v62, v1
	v_sub_f32_e32 v1, v44, v133
	v_mul_f32_e32 v1, 0x3fb8aa3b, v1
	v_exp_f32_e32 v63, v1
	v_sub_f32_e32 v1, v47, v133
	v_mul_f32_e32 v1, 0x3fb8aa3b, v1
	v_exp_f32_e32 v68, v1
	v_sub_f32_e32 v1, v46, v133
	v_mul_f32_e32 v1, 0x3fb8aa3b, v1
	v_exp_f32_e32 v69, v1
	v_sub_f32_e32 v1, v49, v133
	v_mul_f32_e32 v1, 0x3fb8aa3b, v1
	v_exp_f32_e32 v74, v1
	v_sub_f32_e32 v1, v48, v133
	v_mul_f32_e32 v1, 0x3fb8aa3b, v1
	v_exp_f32_e32 v75, v1
	v_sub_f32_e32 v1, v51, v133
	v_mul_f32_e32 v1, 0x3fb8aa3b, v1
	v_exp_f32_e32 v48, v1
	v_sub_f32_e32 v1, v50, v133
	v_mul_f32_e32 v1, 0x3fb8aa3b, v1
	v_exp_f32_e32 v49, v1
	v_sub_f32_e32 v1, v53, v133
	v_mul_f32_e32 v1, 0x3fb8aa3b, v1
	v_exp_f32_e32 v54, v1
	v_sub_f32_e32 v1, v52, v133
	v_mul_f32_e32 v1, 0x3fb8aa3b, v1
	v_exp_f32_e32 v55, v1
	v_sub_f32_e32 v1, v59, v133
	v_mul_f32_e32 v1, 0x3fb8aa3b, v1
	v_exp_f32_e32 v60, v1
	v_sub_f32_e32 v1, v58, v133
	v_mul_f32_e32 v1, 0x3fb8aa3b, v1
	v_exp_f32_e32 v61, v1
	v_sub_f32_e32 v1, v66, v133
	v_mul_f32_e32 v1, 0x3fb8aa3b, v1
	v_exp_f32_e32 v66, v1
	v_sub_f32_e32 v1, v67, v133
	v_sub_f32_e32 v0, v28, v133
	v_mul_f32_e32 v1, 0x3fb8aa3b, v1
	v_mul_f32_e32 v0, 0x3fb8aa3b, v0
	v_exp_f32_e32 v67, v1
	v_sub_f32_e32 v1, v95, v133
	v_exp_f32_e32 v70, v0
	v_mul_f32_e32 v1, 0x3fb8aa3b, v1
	v_exp_f32_e32 v40, v1
	v_sub_f32_e32 v1, v94, v133
	v_mul_f32_e32 v1, 0x3fb8aa3b, v1
	v_exp_f32_e32 v41, v1
	v_sub_f32_e32 v1, v97, v133
	v_add_f32_e32 v0, 0, v70
	v_mul_f32_e32 v1, 0x3fb8aa3b, v1
	v_add_f32_e32 v0, v71, v0
	v_exp_f32_e32 v46, v1
	v_sub_f32_e32 v1, v96, v133
	v_add_f32_e32 v0, v78, v0
	v_mul_f32_e32 v1, 0x3fb8aa3b, v1
	v_add_f32_e32 v0, v79, v0
	v_exp_f32_e32 v47, v1
	v_sub_f32_e32 v1, v99, v133
	v_add_f32_e32 v0, v82, v0
	v_mul_f32_e32 v1, 0x3fb8aa3b, v1
	v_add_f32_e32 v0, v83, v0
	v_exp_f32_e32 v52, v1
	v_sub_f32_e32 v1, v98, v133
	v_add_f32_e32 v0, v84, v0
	v_mul_f32_e32 v1, 0x3fb8aa3b, v1
	v_add_f32_e32 v0, v85, v0
	v_exp_f32_e32 v53, v1
	v_sub_f32_e32 v1, v101, v133
	v_add_f32_e32 v0, v64, v0
	v_mul_f32_e32 v1, 0x3fb8aa3b, v1
	v_add_f32_e32 v0, v65, v0
	v_exp_f32_e32 v58, v1
	v_sub_f32_e32 v1, v100, v133
	v_add_f32_e32 v0, v72, v0
	v_mul_f32_e32 v1, 0x3fb8aa3b, v1
	v_add_f32_e32 v0, v73, v0
	v_exp_f32_e32 v59, v1
	v_sub_f32_e32 v1, v103, v133
	v_add_f32_e32 v0, v76, v0
	v_mul_f32_e32 v1, 0x3fb8aa3b, v1
	v_add_f32_e32 v0, v77, v0
	v_exp_f32_e32 v30, v1
	v_sub_f32_e32 v1, v102, v133
	v_add_f32_e32 v0, v80, v0
	v_mul_f32_e32 v1, 0x3fb8aa3b, v1
	v_add_f32_e32 v0, v81, v0
	v_exp_f32_e32 v31, v1
	v_sub_f32_e32 v1, v105, v133
	v_add_f32_e32 v0, v56, v0
	v_mul_f32_e32 v1, 0x3fb8aa3b, v1
	v_add_f32_e32 v0, v57, v0
	v_exp_f32_e32 v38, v1
	v_sub_f32_e32 v1, v104, v133
	v_add_f32_e32 v0, v62, v0
	v_mul_f32_e32 v1, 0x3fb8aa3b, v1
	v_add_f32_e32 v0, v63, v0
	v_exp_f32_e32 v39, v1
	v_sub_f32_e32 v1, v107, v133
	v_add_f32_e32 v0, v68, v0
	v_mul_f32_e32 v1, 0x3fb8aa3b, v1
	v_add_f32_e32 v0, v69, v0
	v_exp_f32_e32 v44, v1
	v_sub_f32_e32 v1, v106, v133
	v_add_f32_e32 v0, v74, v0
	v_mul_f32_e32 v1, 0x3fb8aa3b, v1
	v_add_f32_e32 v0, v75, v0
	v_exp_f32_e32 v45, v1
	v_sub_f32_e32 v1, v109, v133
	v_add_f32_e32 v0, v48, v0
	v_mul_f32_e32 v1, 0x3fb8aa3b, v1
	v_add_f32_e32 v0, v49, v0
	v_exp_f32_e32 v50, v1
	v_sub_f32_e32 v1, v108, v133
	v_add_f32_e32 v0, v54, v0
	v_mul_f32_e32 v1, 0x3fb8aa3b, v1
	v_add_f32_e32 v0, v55, v0
	v_exp_f32_e32 v51, v1
	v_sub_f32_e32 v1, v111, v133
	v_add_f32_e32 v0, v60, v0
	v_mul_f32_e32 v1, 0x3fb8aa3b, v1
	v_add_f32_e32 v0, v61, v0
	v_exp_f32_e32 v10, v1
	v_sub_f32_e32 v1, v110, v133
	v_add_f32_e32 v0, v66, v0
	v_mul_f32_e32 v1, 0x3fb8aa3b, v1
	v_add_f32_e32 v0, v67, v0
	v_exp_f32_e32 v11, v1
	v_sub_f32_e32 v1, v113, v133
	v_add_f32_e32 v0, v40, v0
	v_mul_f32_e32 v1, 0x3fb8aa3b, v1
	v_add_f32_e32 v0, v41, v0
	v_exp_f32_e32 v28, v1
	v_sub_f32_e32 v1, v112, v133
	v_add_f32_e32 v0, v46, v0
	v_mul_f32_e32 v1, 0x3fb8aa3b, v1
	v_add_f32_e32 v0, v47, v0
	v_exp_f32_e32 v29, v1
	v_sub_f32_e32 v1, v115, v133
	v_add_f32_e32 v0, v52, v0
	v_mul_f32_e32 v1, 0x3fb8aa3b, v1
	v_add_f32_e32 v0, v53, v0
	v_exp_f32_e32 v34, v1
	v_sub_f32_e32 v1, v114, v133
	v_add_f32_e32 v0, v58, v0
	v_mul_f32_e32 v1, 0x3fb8aa3b, v1
	v_add_f32_e32 v0, v59, v0
	v_exp_f32_e32 v35, v1
	v_sub_f32_e32 v1, v117, v133
	v_add_f32_e32 v0, v30, v0
	v_mul_f32_e32 v1, 0x3fb8aa3b, v1
	v_add_f32_e32 v0, v31, v0
	v_exp_f32_e32 v42, v1
	v_sub_f32_e32 v1, v116, v133
	v_add_f32_e32 v0, v38, v0
	v_mul_f32_e32 v1, 0x3fb8aa3b, v1
	v_add_f32_e32 v0, v39, v0
	v_exp_f32_e32 v43, v1
	v_sub_f32_e32 v1, v119, v133
	v_add_f32_e32 v0, v44, v0
	v_mul_f32_e32 v1, 0x3fb8aa3b, v1
	v_add_f32_e32 v0, v45, v0
	v_exp_f32_e32 v4, v1
	v_sub_f32_e32 v1, v118, v133
	v_add_f32_e32 v0, v50, v0
	v_mul_f32_e32 v1, 0x3fb8aa3b, v1
	v_add_f32_e32 v0, v51, v0
	v_exp_f32_e32 v5, v1
	v_sub_f32_e32 v1, v121, v133
	v_add_f32_e32 v0, v10, v0
	v_mul_f32_e32 v1, 0x3fb8aa3b, v1
	v_add_f32_e32 v0, v11, v0
	v_exp_f32_e32 v8, v1
	v_sub_f32_e32 v1, v120, v133
	v_add_f32_e32 v0, v28, v0
	v_mul_f32_e32 v1, 0x3fb8aa3b, v1
	v_add_f32_e32 v0, v29, v0
	v_exp_f32_e32 v9, v1
	v_sub_f32_e32 v1, v123, v133
	v_add_f32_e32 v0, v34, v0
	v_mul_f32_e32 v1, 0x3fb8aa3b, v1
	v_add_f32_e32 v0, v35, v0
	v_exp_f32_e32 v26, v1
	v_sub_f32_e32 v1, v122, v133
	v_add_f32_e32 v0, v42, v0
	v_mul_f32_e32 v1, 0x3fb8aa3b, v1
	v_add_f32_e32 v0, v43, v0
	v_exp_f32_e32 v27, v1
	v_sub_f32_e32 v1, v125, v133
	v_add_f32_e32 v0, v4, v0
	v_mul_f32_e32 v1, 0x3fb8aa3b, v1
	v_add_f32_e32 v0, v5, v0
	v_exp_f32_e32 v32, v1
	v_sub_f32_e32 v1, v124, v133
	v_add_f32_e32 v0, v8, v0
	v_mul_f32_e32 v1, 0x3fb8aa3b, v1
	v_add_f32_e32 v0, v9, v0
	v_exp_f32_e32 v33, v1
	v_add_f32_e32 v0, v26, v0
	v_add_f32_e32 v0, v27, v0
	v_add_f32_e32 v0, v32, v0
	v_add_f32_e32 v1, v33, v0
	v_sub_f32_e32 v0, v127, v133
	v_mul_f32_e32 v0, 0x3fb8aa3b, v0
	v_exp_f32_e32 v0, v0
	v_sub_f32_e32 v6, v6, v133
	v_mul_f32_e32 v6, 0x3fb8aa3b, v6
	v_sub_f32_e32 v7, v7, v133
	v_add_f32_e32 v2, v0, v1
	v_sub_f32_e32 v1, v126, v133
	v_mul_f32_e32 v1, 0x3fb8aa3b, v1
	v_exp_f32_e32 v1, v1
	v_exp_f32_e32 v6, v6
	v_mul_f32_e32 v7, 0x3fb8aa3b, v7
	v_exp_f32_e32 v7, v7
	v_add_f32_e32 v3, v1, v2
	v_sub_f32_e32 v2, v129, v133
	v_mul_f32_e32 v2, 0x3fb8aa3b, v2
	v_exp_f32_e32 v2, v2
	v_sub_f32_e32 v19, v19, v133
	v_mul_f32_e32 v19, 0x3fb8aa3b, v19
	v_exp_f32_e32 v19, v19
	v_add_f32_e32 v24, v2, v3
	v_sub_f32_e32 v3, v128, v133
	v_mul_f32_e32 v3, 0x3fb8aa3b, v3
	v_exp_f32_e32 v3, v3
	ds_read_b128 v[98:101], v15 offset:64768
	ds_read_b128 v[102:105], v86 offset:25088
	ds_read_b128 v[106:109], v86 offset:37632
	v_add_f32_e32 v24, v3, v24
	v_add_f32_e32 v24, v6, v24
	v_add_f32_e32 v25, v7, v24
	v_sub_f32_e32 v24, v131, v133
	v_mul_f32_e32 v24, 0x3fb8aa3b, v24
	v_exp_f32_e32 v24, v24
	s_nop 0
	v_add_f32_e32 v36, v24, v25
	v_sub_f32_e32 v25, v130, v133
	v_mul_f32_e32 v25, 0x3fb8aa3b, v25
	v_exp_f32_e32 v25, v25
	s_nop 0
	v_add_f32_e32 v36, v25, v36
	ds_bpermute_b32 v94, v132, v36
	s_waitcnt lgkmcnt(0)
	v_add_f32_e32 v36, v36, v94
	ds_bpermute_b32 v94, v134, v36
	s_waitcnt lgkmcnt(0)
	v_add_f32_e32 v36, v36, v94
	v_add_f32_e32 v19, v19, v36
	v_rcp_f32_e32 v36, v19
	s_nop 0
	v_pk_mul_f32 v[70:71], v[70:71], v[36:37] op_sel_hi:[1,0]
	v_pk_mul_f32 v[78:79], v[78:79], v[36:37] op_sel_hi:[1,0]
	v_cvt_pk_bf16_f32 v94, v70, v71
	v_cvt_pk_bf16_f32 v95, v78, v79
	v_pk_mul_f32 v[70:71], v[82:83], v[36:37] op_sel_hi:[1,0]
	v_pk_mul_f32 v[78:79], v[84:85], v[36:37] op_sel_hi:[1,0]
	ds_read_b128 v[82:85], v15 offset:52224
	v_pk_mul_f32 v[64:65], v[64:65], v[36:37] op_sel_hi:[1,0]
	v_cvt_pk_bf16_f32 v96, v70, v71
	v_pk_mul_f32 v[72:73], v[72:73], v[36:37] op_sel_hi:[1,0]
	v_cvt_pk_bf16_f32 v70, v64, v65
	v_pk_mul_f32 v[64:65], v[76:77], v[36:37] op_sel_hi:[1,0]
	v_pk_mul_f32 v[76:77], v[80:81], v[36:37] op_sel_hi:[1,0]
	v_cvt_pk_bf16_f32 v97, v78, v79
	v_cvt_pk_bf16_f32 v71, v72, v73
	v_cvt_pk_bf16_f32 v73, v76, v77
	ds_read_b128 v[76:79], v15 offset:52288
	s_waitcnt lgkmcnt(1)
	v_mfma_f32_16x16x32_bf16 v[82:85], v[82:85], v[94:97], 0
	v_cvt_pk_bf16_f32 v72, v64, v65
	v_pk_mul_f32 v[56:57], v[56:57], v[36:37] op_sel_hi:[1,0]
	v_pk_mul_f32 v[64:65], v[62:63], v[36:37] op_sel_hi:[1,0]
	s_waitcnt lgkmcnt(0)
	v_mfma_f32_16x16x32_bf16 v[76:79], v[76:79], v[70:73], v[82:85]
	s_nop 2
	ds_read_b128 v[80:83], v15 offset:64832
	v_cvt_pk_bf16_f32 v62, v56, v57
	v_pk_mul_f32 v[56:57], v[68:69], v[36:37] op_sel_hi:[1,0]
	v_mfma_f32_16x16x32_bf16 v[98:101], v[98:101], v[94:97], 0
	v_mul_f32_e64 v68, v74, v36
	v_mul_f32_e64 v69, v75, v36
	v_cvt_pk_bf16_f32 v63, v64, v65
	v_cvt_pk_bf16_f32 v64, v56, v57
	s_waitcnt lgkmcnt(0)
	v_mfma_f32_16x16x32_bf16 v[80:83], v[80:83], v[70:73], v[98:101]
	v_cvt_pk_bf16_f32 v65, v68, v69
	s_nop 1
	ds_read_b128 v[98:101], v86 offset:25152
	v_pk_mul_f32 v[48:49], v[48:49], v[36:37] op_sel_hi:[1,0]
	v_mfma_f32_16x16x32_bf16 v[102:105], v[102:105], v[94:97], 0
	v_mul_f32_e64 v56, v54, v36
	v_mul_f32_e64 v57, v55, v36
	v_cvt_pk_bf16_f32 v54, v48, v49
	v_pk_mul_f32 v[48:49], v[60:61], v[36:37] op_sel_hi:[1,0]
	s_waitcnt lgkmcnt(0)
	v_mfma_f32_16x16x32_bf16 v[98:101], v[98:101], v[70:73], v[102:105]
	v_mul_f32_e64 v60, v66, v36
	v_mul_f32_e64 v61, v67, v36
	s_nop 0
	ds_read_b128 v[102:105], v86 offset:37696
	v_mfma_f32_16x16x32_bf16 v[94:97], v[106:109], v[94:97], 0
	v_cvt_pk_bf16_f32 v55, v56, v57
	v_cvt_pk_bf16_f32 v56, v48, v49
	v_cvt_pk_bf16_f32 v57, v60, v61
	s_waitcnt lgkmcnt(0)
	v_mfma_f32_16x16x32_bf16 v[70:73], v[102:105], v[70:73], v[94:97]
	v_mul_f32_e64 v40, v40, v36
	v_mul_f32_e64 v41, v41, v36
	s_nop 0
	ds_read_b128 v[94:97], v15 offset:52352
	v_pk_mul_f32 v[48:49], v[46:47], v[36:37] op_sel_hi:[1,0]
	s_waitcnt lgkmcnt(0)
	v_mfma_f32_16x16x32_bf16 v[74:77], v[94:97], v[62:65], v[76:79]
	ds_read_b128 v[94:97], v15 offset:64896
	v_cvt_pk_bf16_f32 v46, v40, v41
	v_pk_mul_f32 v[40:41], v[52:53], v[36:37] op_sel_hi:[1,0]
	s_waitcnt lgkmcnt(0)
	v_mfma_f32_16x16x32_bf16 v[78:81], v[94:97], v[62:65], v[80:83]
	s_nop 2
	ds_read_b128 v[82:85], v86 offset:25216
	ds_read_b128 v[94:97], v86 offset:37760
	s_waitcnt lgkmcnt(1)
	v_mfma_f32_16x16x32_bf16 v[82:85], v[82:85], v[62:65], v[98:101]
	ds_read_b128 v[66:69], v15 offset:52416
	v_pk_mul_f32 v[52:53], v[58:59], v[36:37] op_sel_hi:[1,0]
	v_cvt_pk_bf16_f32 v47, v48, v49
	s_waitcnt lgkmcnt(1)
	v_mfma_f32_16x16x32_bf16 v[62:65], v[94:97], v[62:65], v[70:73]
	v_cvt_pk_bf16_f32 v48, v40, v41
	v_cvt_pk_bf16_f32 v49, v52, v53
	v_pk_mul_f32 v[30:31], v[30:31], v[36:37] op_sel_hi:[1,0]
	ds_read_b128 v[70:73], v15 offset:64960
	s_waitcnt lgkmcnt(1)
	v_mfma_f32_16x16x32_bf16 v[66:69], v[66:69], v[54:57], v[74:77]
	v_mul_f32_e64 v40, v38, v36
	v_mul_f32_e64 v41, v39, v36
	v_cvt_pk_bf16_f32 v38, v30, v31
	ds_read_b128 v[74:77], v86 offset:25280
	s_waitcnt lgkmcnt(1)
	v_mfma_f32_16x16x32_bf16 v[70:73], v[70:73], v[54:57], v[78:81]
	s_nop 2
	ds_read_b128 v[78:81], v86 offset:37824
	ds_read_b128 v[58:61], v15 offset:52480
	s_waitcnt lgkmcnt(2)
	v_mfma_f32_16x16x32_bf16 v[74:77], v[74:77], v[54:57], v[82:85]
	v_mul_f32_e64 v30, v44, v36
	v_mul_f32_e64 v31, v45, v36
	v_pk_mul_f32 v[44:45], v[50:51], v[36:37] op_sel_hi:[1,0]
	v_cvt_pk_bf16_f32 v39, v40, v41
	s_waitcnt lgkmcnt(1)
	v_mfma_f32_16x16x32_bf16 v[54:57], v[78:81], v[54:57], v[62:65]
	v_cvt_pk_bf16_f32 v40, v30, v31
	v_cvt_pk_bf16_f32 v41, v44, v45
	s_nop 0
	ds_read_b128 v[62:65], v15 offset:65024
	s_waitcnt lgkmcnt(1)
	v_mfma_f32_16x16x32_bf16 v[58:61], v[58:61], v[46:49], v[66:69]
	v_mul_f32_e64 v10, v10, v36
	v_mul_f32_e64 v11, v11, v36
	v_pk_mul_f32 v[30:31], v[28:29], v[36:37] op_sel_hi:[1,0]
	v_cvt_pk_bf16_f32 v28, v10, v11
	s_waitcnt lgkmcnt(0)
	v_mfma_f32_16x16x32_bf16 v[62:65], v[62:65], v[46:49], v[70:73]
	ds_read_b128 v[66:69], v86 offset:25344
	s_nop 1
	ds_read_b128 v[70:73], v86 offset:37888
	s_waitcnt lgkmcnt(1)
	v_mfma_f32_16x16x32_bf16 v[66:69], v[66:69], v[46:49], v[74:77]
	ds_read_b128 v[50:53], v15 offset:52544
	v_pk_mul_f32 v[10:11], v[34:35], v[36:37] op_sel_hi:[1,0]
	v_pk_mul_f32 v[34:35], v[42:43], v[36:37] op_sel_hi:[1,0]
	s_waitcnt lgkmcnt(1)
	v_mfma_f32_16x16x32_bf16 v[46:49], v[70:73], v[46:49], v[54:57]
	v_cvt_pk_bf16_f32 v29, v30, v31
	v_cvt_pk_bf16_f32 v30, v10, v11
	v_cvt_pk_bf16_f32 v31, v34, v35
	ds_read_b128 v[54:57], v15 offset:65088
	s_waitcnt lgkmcnt(1)
	v_mfma_f32_16x16x32_bf16 v[50:53], v[50:53], v[38:41], v[58:61]
	v_mul_f32_e64 v4, v4, v36
	v_mul_f32_e64 v5, v5, v36
	v_pk_mul_f32 v[10:11], v[8:9], v[36:37] op_sel_hi:[1,0]
	ds_read_b128 v[58:61], v86 offset:25408
	s_waitcnt lgkmcnt(1)
	v_mfma_f32_16x16x32_bf16 v[54:57], v[54:57], v[38:41], v[62:65]
	s_nop 2
	ds_read_b128 v[62:65], v86 offset:37952
	ds_read_b128 v[42:45], v15 offset:52608
	s_waitcnt lgkmcnt(2)
	v_mfma_f32_16x16x32_bf16 v[58:61], v[58:61], v[38:41], v[66:69]
	v_cvt_pk_bf16_f32 v8, v4, v5
	v_pk_mul_f32 v[4:5], v[26:27], v[36:37] op_sel_hi:[1,0]
	v_pk_mul_f32 v[26:27], v[32:33], v[36:37] op_sel_hi:[1,0]
	s_waitcnt lgkmcnt(1)
	v_mfma_f32_16x16x32_bf16 v[38:41], v[62:65], v[38:41], v[46:49]
	v_cvt_pk_bf16_f32 v9, v10, v11
	v_cvt_pk_bf16_f32 v10, v4, v5
	s_nop 0
	ds_read_b128 v[46:49], v15 offset:65152
	s_waitcnt lgkmcnt(1)
	v_mfma_f32_16x16x32_bf16 v[42:45], v[42:45], v[28:31], v[50:53]
	v_cvt_pk_bf16_f32 v11, v26, v27
	v_pk_mul_f32 v[0:1], v[0:1], v[36:37] op_sel_hi:[1,0]
	v_pk_mul_f32 v[2:3], v[2:3], v[36:37] op_sel_hi:[1,0]
	s_waitcnt lgkmcnt(0)
	v_mfma_f32_16x16x32_bf16 v[46:49], v[46:49], v[28:31], v[54:57]
	ds_read_b128 v[50:53], v86 offset:25472
	s_nop 1
	ds_read_b128 v[54:57], v86 offset:38016
	s_waitcnt lgkmcnt(1)
	v_mfma_f32_16x16x32_bf16 v[50:53], v[50:53], v[28:31], v[58:61]
	ds_read_b128 v[32:35], v15 offset:52672
	v_cvt_pk_bf16_f32 v0, v0, v1
	v_cvt_pk_bf16_f32 v1, v2, v3
	s_waitcnt lgkmcnt(1)
	v_mfma_f32_16x16x32_bf16 v[28:31], v[54:57], v[28:31], v[38:41]
	v_mul_f32_e64 v2, v6, v36
	v_mul_f32_e64 v3, v7, v36
	v_pk_mul_f32 v[4:5], v[24:25], v[36:37] op_sel_hi:[1,0]
	v_cvt_pk_bf16_f32 v2, v2, v3
	ds_read_b128 v[38:41], v15 offset:65216
	s_waitcnt lgkmcnt(1)
	v_mfma_f32_16x16x32_bf16 v[32:35], v[32:35], v[8:11], v[42:45]
	v_cvt_pk_bf16_f32 v3, v4, v5
	s_nop 1
	ds_read_b128 v[42:45], v86 offset:25536
	s_waitcnt lgkmcnt(1)
	v_mfma_f32_16x16x32_bf16 v[38:41], v[38:41], v[8:11], v[46:49]
	s_nop 2
	ds_read_b128 v[46:49], v86 offset:38080
	ds_read_b128 v[4:7], v15 offset:52736
	ds_read_b128 v[24:27], v15 offset:65280
	s_waitcnt lgkmcnt(3)
	v_mfma_f32_16x16x32_bf16 v[42:45], v[42:45], v[8:11], v[50:53]
	s_waitcnt lgkmcnt(2)
	v_mfma_f32_16x16x32_bf16 v[8:11], v[46:49], v[8:11], v[28:31]
	s_nop 2
	ds_read_b128 v[28:31], v86 offset:25600
	s_waitcnt lgkmcnt(2)
	v_mfma_f32_16x16x32_bf16 v[4:7], v[4:7], v[0:3], v[32:35]
	s_nop 2
	ds_read_b128 v[32:35], v86 offset:38144
	s_waitcnt lgkmcnt(2)
	v_mfma_f32_16x16x32_bf16 v[24:27], v[24:27], v[0:3], v[38:41]
	s_nop 1
	v_cvt_pk_bf16_f32 v4, v4, v5
	v_cvt_pk_bf16_f32 v5, v6, v7
	s_waitcnt lgkmcnt(1)
	v_mfma_f32_16x16x32_bf16 v[28:31], v[28:31], v[0:3], v[42:45]
	s_waitcnt lgkmcnt(0)
	v_mfma_f32_16x16x32_bf16 v[0:3], v[32:35], v[0:3], v[8:11]
	v_cvt_pk_bf16_f32 v6, v24, v25
	v_cvt_pk_bf16_f32 v7, v26, v27
	s_nop 0
	v_lshl_add_u64 v[8:9], v[22:23], 0, s[0:1]
	global_store_dwordx4 v[8:9], v[4:7], off
	s_nop 1
	v_cvt_pk_bf16_f32 v4, v28, v29
	v_cvt_pk_bf16_f32 v5, v30, v31
	v_cvt_pk_bf16_f32 v6, v0, v1
	v_cvt_pk_bf16_f32 v7, v2, v3
	global_store_dwordx4 v[8:9], v[4:7], off offset:64
	s_cbranch_vccnz .LBB0_679
